# A units: per-layer lambda scalar computed by the first unit of a layer and kept in a spare v255 lane; later units skip the 4 vector loads, the round-trip wait and the cross-lane reduction
# speedup vs baseline: 1.0032x; 1.0032x over previous
; #define LAS __attribute__((address_space(3)))
; __global__ void __launch_bounds__(512, 2) fwd_kernel(Args a) {
;     ...
;           if (G == 256) { const int x = blockIdx.x & 7, jx = blockIdx.x >> 3;
;               for (int r = 0; r < 8; ++r) attn_unit_A(P, (x + 8 * r) * 33 + jx, (LAS char*)lds);
;               if (jx < 8) attn_unit_A(P, (x + 8 * jx) * 33 + 32, (LAS char*)lds);
;           } else { for (int u = blockIdx.x; u < NUA; u += G) attn_unit_A(P, u, (LAS char*)lds); }
.Lp4prio_skip:
	v_writelane_b32 v255, 0, 59
	v_readlane_b32 s64, v252, 16
	v_readlane_b32 s65, v252, 17
	v_readlane_b32 s66, v252, 18
	v_readlane_b32 s67, v252, 19
	v_readlane_b32 s63, v255, 47
	s_cbranch_vccz .LBB0_623
	v_readlane_b32 s0, v253, 56
	v_readlane_b32 s1, v253, 57
	s_andn2_b64 vcc, exec, s[0:1]
	s_cbranch_vccnz .LBB0_622
	s_mov_b32 s12, s2
	s_branch .LBB0_531

; #define LAS __attribute__((address_space(3)))
; __device__ __forceinline__ void attn_unit_A(const AttnP& P, int u, LAS char* lds) {
;     ...
;     const int b = u / (4 * 33), h = (u / 33) & 3, qb = u % 33;
;     const int qs = w >> 1, mp = w & 1;
;     const int qtok0 = qb * 128 + qs * 32, tq = qtok0 + r32;
;     constexpr int nt = 65;
;     LAS float* tab = (LAS float*)(lds + ATAB);
;     for (int i = tid; i < 257; i += 512) tab[i] = P.t5[t5_bucket(i - 128) * 12 + h] * LOG2E;
;     bf16x8 qr[4];
;     { const int qt = tq > LT - 1 ? LT - 1 : tq; const bf16_t* qp = P.proj + (size_t)(b * LT + qt) * INC + h * 128 + mp * 64 + hi * 8;
; #pragma unroll
;       for (int ds = 0; ds < 4; ++ds) qr[ds] = *(const bf16x8*)(qp + ds * 16); }
;     f32x16 o[4];
; #pragma unroll
;     for (int d = 0; d < 4; ++d)
; #pragma unroll
;         for (int r = 0; r < 16; ++r) o[d][r] = 0.f;
;     const int lrow = tid >> 3, lch = tid & 7;
;     u32x4 pre[4];
;     const bf16_t* pb = P.proj + (size_t)b * LT * INC + lch * 8 + h * 128;
;     ...
;     float a1 = P.lq1[lane] * P.lk1[lane], a2 = P.lq2[lane] * P.lk2[lane];
; #pragma unroll
;     for (int s = 1; s < 64; s <<= 1) { a1 += __shfl_xor(a1, s); a2 += __shfl_xor(a2, s); }
;     unsigned lamu = __builtin_amdgcn_readfirstlane(__float_as_uint(__expf(a1) - __expf(a2) + lam_init_of(P.layer))); asm volatile("" : "+s"(lamu));
;     const float lam = __uint_as_float(lamu);
.Latt1_lamfast:
	v_and_b32_e32 v171, 63, v34
	v_lshlrev_b32_e32 v0, 2, v171
	v_and_b32_e32 v5, 64, v237
	v_xor_b32_e32 v6, 1, v237
	v_add_u32_e32 v5, 64, v5
	v_cmp_lt_i32_e32 vcc, v6, v5
	v_xor_b32_e32 v7, 2, v237
	v_xor_b32_e32 v8, 4, v237
	v_cndmask_b32_e32 v6, v237, v6, vcc
	v_lshlrev_b32_e32 v166, 2, v6
	v_cmp_lt_i32_e32 vcc, v7, v5
	v_xor_b32_e32 v9, 8, v237
	v_xor_b32_e32 v10, 16, v237
	v_cndmask_b32_e32 v7, v237, v7, vcc
	v_lshlrev_b32_e32 v167, 2, v7
	v_cmp_lt_i32_e32 vcc, v8, v5
	s_lshr_b32 s15, s13, 3
	s_mul_i32 s0, s15, 33
	s_sub_i32 s0, s35, s0
	s_ashr_i32 s38, s27, 2
	s_lshl_b32 s0, s0, 7
	s_andn2_b32 s38, s38, 31
	v_and_b32_e32 v173, 31, v34
	s_add_i32 s14, s38, s0
	s_lshr_b32 s26, s13, 5
	v_or_b32_e32 v172, s14, v173
	s_mul_i32 s13, s26, 0x1010
	s_bfe_u32 s34, s27, 0x10006
	s_lshl_b32 s80, s16, 8
	v_lshrrev_b32_e32 v68, 5, v171
	v_xor_b32_e32 v11, 32, v237
	v_cndmask_b32_e32 v3, v237, v8, vcc
	v_lshlrev_b32_e32 v168, 2, v3
	v_cmp_lt_i32_e32 vcc, v9, v5
	v_cndmask_b32_e32 v6, v237, v9, vcc
	v_lshlrev_b32_e32 v169, 2, v6
	v_cmp_lt_i32_e32 vcc, v10, v5
	v_cndmask_b32_e32 v6, v237, v10, vcc
	v_lshlrev_b32_e32 v170, 2, v6
	v_mov_b64_e32 v[6:7], s[70:71]
	v_cmp_lt_i32_e32 vcc, v11, v5
	v_min_i32_e32 v0, 0x100f, v172
	v_add_u32_e32 v0, s13, v0
	v_mad_i64_i32 v[6:7], s[0:1], v0, s51, v[6:7]
	v_lshl_add_u64 v[6:7], v[6:7], 0, s[80:81]
	s_lshl_b32 s80, s34, 7
	v_lshl_add_u64 v[6:7], v[6:7], 0, s[80:81]
	v_lshlrev_b32_e32 v0, 4, v68
	v_lshl_add_u64 v[6:7], v[6:7], 0, v[0:1]
	global_load_dwordx4 v[140:143], v[6:7], off
	global_load_dwordx4 v[136:139], v[6:7], off offset:32
	global_load_dwordx4 v[132:135], v[6:7], off offset:64
	global_load_dwordx4 v[128:131], v[6:7], off offset:96
	v_cndmask_b32_e32 v5, v237, v11, vcc
	v_lshlrev_b32_e32 v165, 2, v5
	s_lshl_b32 s16, s16, 7
	s_mul_hi_u32 s1, s26, 0x1e1e000
	s_mul_i32 s26, s26, 0x1e1e000
	s_add_u32 s0, s70, s26
	v_lshlrev_b32_e32 v7, 4, v34
	s_addc_u32 s1, s71, s1
	v_and_b32_e32 v160, 0x70, v7
	v_mov_b32_e32 v161, v1
	v_lshl_add_u64 v[8:9], s[0:1], 0, v[160:161]
	v_ashrrev_i32_e32 v35, 3, v34
	s_lshl_b32 s80, s16, 1
	v_lshl_add_u64 v[162:163], v[8:9], 0, s[80:81]
	s_waitcnt lgkmcnt(0)
	v_readlane_b32 s40, v255, 60
	s_branch .Latt1_lamjoin
.LBB0_637:
	s_or_b64 exec, exec, s[0:1]
	v_readlane_b32 s0, v255, 59
	s_nop 3
	s_cmp_lg_u32 s0, 0
	s_cbranch_scc1 .Latt1_lamfast
	v_and_b32_e32 v171, 63, v34
	v_lshlrev_b32_e32 v0, 2, v171
	global_load_dword v2, v0, s[48:49]
	global_load_dword v3, v0, s[42:43]
	global_load_dword v4, v0, s[52:53]
	s_nop 0
	global_load_dword v0, v0, s[54:55]
	v_and_b32_e32 v5, 64, v237
	v_xor_b32_e32 v6, 1, v237
	v_add_u32_e32 v5, 64, v5
	v_cmp_lt_i32_e32 vcc, v6, v5
	v_xor_b32_e32 v7, 2, v237
	v_xor_b32_e32 v8, 4, v237
	v_cndmask_b32_e32 v6, v237, v6, vcc
	v_lshlrev_b32_e32 v166, 2, v6
	v_cmp_lt_i32_e32 vcc, v7, v5
	v_xor_b32_e32 v9, 8, v237
	v_xor_b32_e32 v10, 16, v237
	v_cndmask_b32_e32 v7, v237, v7, vcc
	v_lshlrev_b32_e32 v167, 2, v7
	v_cmp_lt_i32_e32 vcc, v8, v5
	s_lshr_b32 s15, s13, 3
	s_mul_i32 s0, s15, 33
	s_sub_i32 s0, s35, s0
	s_ashr_i32 s38, s27, 2
	s_lshl_b32 s0, s0, 7
	s_andn2_b32 s38, s38, 31
	v_and_b32_e32 v173, 31, v34
	s_add_i32 s14, s38, s0
	s_lshr_b32 s26, s13, 5
	v_or_b32_e32 v172, s14, v173
	s_mul_i32 s13, s26, 0x1010
	s_bfe_u32 s34, s27, 0x10006
	s_lshl_b32 s80, s16, 8
	s_waitcnt vmcnt(0)
	v_lshrrev_b32_e32 v68, 5, v171
	v_xor_b32_e32 v11, 32, v237
	v_mul_f32_e32 v6, v2, v3
	ds_bpermute_b32 v6, v166, v6
	v_mul_f32_e32 v12, v4, v0
	ds_bpermute_b32 v12, v166, v12
	s_waitcnt lgkmcnt(1)
	v_fmac_f32_e32 v6, v2, v3
	v_cndmask_b32_e32 v3, v237, v8, vcc
	s_waitcnt lgkmcnt(0)
	v_fmac_f32_e32 v12, v4, v0
	ds_bpermute_b32 v0, v167, v6
	ds_bpermute_b32 v2, v167, v12
	v_lshlrev_b32_e32 v168, 2, v3
	v_cmp_lt_i32_e32 vcc, v9, v5
	s_waitcnt lgkmcnt(1)
	v_add_f32_e32 v0, v6, v0
	s_waitcnt lgkmcnt(0)
	v_add_f32_e32 v2, v12, v2
	ds_bpermute_b32 v3, v168, v0
	ds_bpermute_b32 v4, v168, v2
	v_cndmask_b32_e32 v6, v237, v9, vcc
	v_lshlrev_b32_e32 v169, 2, v6
	v_cmp_lt_i32_e32 vcc, v10, v5
	s_waitcnt lgkmcnt(1)
	v_add_f32_e32 v0, v0, v3
	s_waitcnt lgkmcnt(0)
	v_add_f32_e32 v2, v2, v4
	ds_bpermute_b32 v3, v169, v0
	ds_bpermute_b32 v4, v169, v2
	v_cndmask_b32_e32 v6, v237, v10, vcc
	v_lshlrev_b32_e32 v170, 2, v6
	v_mov_b64_e32 v[6:7], s[70:71]
	s_waitcnt lgkmcnt(1)
	v_add_f32_e32 v0, v0, v3
	s_waitcnt lgkmcnt(0)
	v_add_f32_e32 v3, v2, v4
	ds_bpermute_b32 v2, v170, v0
	ds_bpermute_b32 v4, v170, v3
	v_cmp_lt_i32_e32 vcc, v11, v5
	s_waitcnt lgkmcnt(1)
	v_add_f32_e32 v2, v0, v2
	v_min_i32_e32 v0, 0x100f, v172
	v_add_u32_e32 v0, s13, v0
	v_mad_i64_i32 v[6:7], s[0:1], v0, s51, v[6:7]
	v_lshl_add_u64 v[6:7], v[6:7], 0, s[80:81]
	s_lshl_b32 s80, s34, 7
	v_lshl_add_u64 v[6:7], v[6:7], 0, s[80:81]
	v_lshlrev_b32_e32 v0, 4, v68
	v_lshl_add_u64 v[6:7], v[6:7], 0, v[0:1]
	global_load_dwordx4 v[140:143], v[6:7], off
	global_load_dwordx4 v[136:139], v[6:7], off offset:32
	global_load_dwordx4 v[132:135], v[6:7], off offset:64
	global_load_dwordx4 v[128:131], v[6:7], off offset:96
	v_cndmask_b32_e32 v5, v237, v11, vcc
	v_lshlrev_b32_e32 v165, 2, v5
	s_waitcnt lgkmcnt(0)
	v_add_f32_e32 v3, v3, v4
	ds_bpermute_b32 v4, v165, v2
	ds_bpermute_b32 v5, v165, v3
	s_cmp_lt_i32 s62, 1
	v_mov_b32_e32 v6, 0x3e4ccccd
	s_cbranch_scc1 .LBB0_642
	s_cmp_lg_u32 s62, 1
	s_mov_b64 s[0:1], -1
	s_cbranch_scc0 .LBB0_640
	s_mov_b64 s[0:1], 0

; #define A_ISSUE(t) do { int tok_ = 64 * (t) + lrow; tok_ = tok_ > LT - 1 ? LT - 1 : tok_; const bf16_t* src_ = pb + (size_t)tok_ * INC; \
;         pre[0] = *(const u32x4*)(src_ + 512); pre[1] = *(const u32x4*)(src_ + 576); pre[2] = *(const u32x4*)(src_ + 1024); pre[3] = *(const u32x4*)(src_ + 1088); } while (0)
; #define A_WRITE(bufo) do { LAS char* d_ = lds + (bufo); \
;         *(LAS u32x4*)(d_ + lrow * AKP + lch * 16) = pre[0]; *(LAS u32x4*)(d_ + AKS + lrow * AKP + lch * 16) = pre[1]; \
;         *(LAS u32x4*)(d_ + 2 * AKS + lrow * AVP + lch * 16) = pre[2]; *(LAS u32x4*)(d_ + 2 * AKS + AVS + lrow * AVP + lch * 16) = pre[3]; } while (0)
; #define A_BAR() asm volatile("s_waitcnt lgkmcnt(0)\n\ts_barrier" ::: "memory")
; __device__ __forceinline__ void attn_unit_A(const AttnP& P, int u, LAS char* lds) {
;     ...
;     float a1 = P.lq1[lane] * P.lk1[lane], a2 = P.lq2[lane] * P.lk2[lane];
; #pragma unroll
;     for (int s = 1; s < 64; s <<= 1) { a1 += __shfl_xor(a1, s); a2 += __shfl_xor(a2, s); }
;     unsigned lamu = __builtin_amdgcn_readfirstlane(__float_as_uint(__expf(a1) - __expf(a2) + lam_init_of(P.layer))); asm volatile("" : "+s"(lamu));
;     const float lam = __uint_as_float(lamu);
;     A_ISSUE(0);
;     __syncthreads();
;     A_WRITE(0); A_ISSUE(1);
;     A_BAR();
;     f32x16 sa0, sa1, negc; float lrun = 0.f;
;     const int vrow = 4 * hi + ((lane & 15) >> 2), vcolb = 32 * ((lane >> 4) & 1) + 8 * (lane & 3);
;     int clsk;
;     ...
;     {
;         A_QK(sa0, sa1, 0);
;         clsk = A_CLS(0);
;         if (clsk == 1) A_NEAR(sa0, sa1, 0);
;         else { const float c0 = A_CVAL(clsk);
; #pragma unroll
;             for (int r = 0; r < 16; ++r) { sa0[r] += c0; sa1[r] += c0; } }
.LBB0_642:
	s_waitcnt lgkmcnt(1)
	v_add_f32_e32 v2, v2, v4
	s_waitcnt lgkmcnt(0)
	v_add_f32_e32 v3, v3, v5
	v_mul_f32_e32 v2, 0x3fb8aa3b, v2
	v_mul_f32_e32 v3, 0x3fb8aa3b, v3
	v_exp_f32_e32 v2, v2
	v_exp_f32_e32 v3, v3
	s_lshl_b32 s16, s16, 7
	s_mul_hi_u32 s1, s26, 0x1e1e000
	s_mul_i32 s26, s26, 0x1e1e000
	s_add_u32 s0, s70, s26
	v_lshlrev_b32_e32 v7, 4, v34
	s_addc_u32 s1, s71, s1
	v_and_b32_e32 v160, 0x70, v7
	v_mov_b32_e32 v161, v1
	v_sub_f32_e32 v2, v2, v3
	v_lshl_add_u64 v[8:9], s[0:1], 0, v[160:161]
	v_ashrrev_i32_e32 v35, 3, v34
	s_lshl_b32 s80, s16, 1
	v_add_f32_e32 v2, v2, v6
	v_lshl_add_u64 v[162:163], v[8:9], 0, s[80:81]
	v_readfirstlane_b32 s40, v2
	s_nop 1
	v_writelane_b32 v255, s40, 60
	v_writelane_b32 v255, 1, 59
.Latt1_lamjoin:
	v_min_i32_e32 v2, 0x100f, v35
	v_mad_i64_i32 v[14:15], s[0:1], v2, s51, v[162:163]
	global_load_dwordx4 v[2:5], v[14:15], off offset:1024
	global_load_dwordx4 v[6:9], v[14:15], off offset:1152
	global_load_dwordx4 v[10:13], v[14:15], off offset:2048
	s_nop 0
	global_load_dwordx4 v[14:17], v[14:15], off offset:2176
	s_movk_i32 s0, 0x90
	v_mul_lo_u32 v178, v35, s0
	v_add3_u32 v18, 0, v178, v160
	s_barrier
	s_mov_b64 s[30:31], -1
	s_mov_b64 s[28:29], 0
	s_waitcnt vmcnt(3)
	ds_write_b128 v18, v[2:5]
	s_waitcnt vmcnt(2)
	ds_write_b128 v18, v[6:9] offset:9216
	v_mad_u64_u32 v[2:3], s[0:1], v35, 48, v[18:19]
	s_waitcnt vmcnt(1)
	ds_write_b128 v2, v[10:13] offset:18432
	s_waitcnt vmcnt(0)
	ds_write_b128 v2, v[14:17] offset:30720
	v_min_i32_e32 v2, 0xfcf, v35
	v_add_u32_e32 v2, 64, v2
	v_mad_i64_i32 v[2:3], s[0:1], v2, s51, v[162:163]
	global_load_dwordx4 v[156:159], v[2:3], off offset:1024
	global_load_dwordx4 v[152:155], v[2:3], off offset:1152
	global_load_dwordx4 v[148:151], v[2:3], off offset:2048
	global_load_dwordx4 v[144:147], v[2:3], off offset:2176
	s_mul_i32 s0, s34, 0x2400
	v_mul_u32_u24_e32 v2, 0x90, v173
	s_add_i32 s0, s0, 0
	s_waitcnt lgkmcnt(0)
	s_barrier
	v_add3_u32 v174, s0, v2, v0
	ds_read_b128 v[2:5], v174 offset:4608
	ds_read_b128 v[6:9], v174
	ds_read_b128 v[36:39], v174 offset:32
	ds_read_b128 v[40:43], v174 offset:4640
	s_waitcnt lgkmcnt(2)
	v_mfma_f32_32x32x16_bf16 v[18:33], v[6:9], v[140:143], 0
	s_cmpk_lt_i32 s14, 0xff62
	s_cselect_b32 s0, 2, 1
	s_cmpk_lt_i32 s14, 0xbf
	s_cselect_b32 s39, s0, 0
	s_mov_b64 s[0:1], 0
	s_cmp_gt_i32 s39, 1
	v_mfma_f32_32x32x16_bf16 v[2:17], v[2:5], v[140:143], 0
	s_waitcnt lgkmcnt(1)
	v_mfma_f32_32x32x16_bf16 v[18:33], v[36:39], v[136:139], v[18:33]
	s_waitcnt lgkmcnt(0)
	v_mfma_f32_32x32x16_bf16 v[2:17], v[40:43], v[136:139], v[2:17]
	ds_read_b128 v[36:39], v174 offset:64
	ds_read_b128 v[40:43], v174 offset:4672
	s_waitcnt lgkmcnt(1)
	v_mfma_f32_32x32x16_bf16 v[18:33], v[36:39], v[132:135], v[18:33]
	s_waitcnt lgkmcnt(0)
	v_mfma_f32_32x32x16_bf16 v[2:17], v[40:43], v[132:135], v[2:17]
	ds_read_b128 v[36:39], v174 offset:96
	ds_read_b128 v[40:43], v174 offset:4704
	s_waitcnt lgkmcnt(1)
	v_mfma_f32_32x32x16_bf16 v[18:33], v[36:39], v[128:131], v[18:33]
	s_waitcnt lgkmcnt(0)
	v_mfma_f32_32x32x16_bf16 v[2:17], v[40:43], v[128:131], v[2:17]
	s_cbranch_scc0 .LBB0_644
	s_mov_b64 s[30:31], 0
	s_mov_b64 s[28:29], -1
